# prep_weights: W_O / FFN2 weight conversion moved from phase 0 into the in-projection phase tail of workgroups 128-255 (they have one GEMM tile less and were idle at the grid barrier)
# speedup vs baseline: 1.0082x; 1.0010x over previous
; template <class Epi, class Sched, bool ALIGN_EPI = false, bool SP2 = false>
; __device__ __forceinline__ void gemm_phase(PG8_LAS unsigned char* lds, const Gemm g, const Sched& S, const Epi& E) {
;     ...
;     PG8_WAIT_V(0);
;     if constexpr (!ALIGN_EPI) { if (wr == 0) PG8_BAR; }
;     PG8_BAR;
; __device__ __forceinline__ void prep_weights(lptr L, const Params& P, int l) {
;     const int tid = otid(), lane = tid & 63, wave = tid >> 6;
;     const int gw = blockIdx.x * 8 + wave, NGW = gridDim.x * 8;
;     const lptr scr = L + wave * 8704;
;     unsigned char* ws = P.ws;
; #pragma unroll 1
;     for (int mi = 0; mi < 14; ++mi) {
;         const float* W; int K, N, mode = 0; bf16_t* WT;
;         switch (mi) {
;             case 0: W = P.in[4] + (size_t)l * DM * 2 * DFF; K = DM; N = 2 * DFF; WT = (bf16_t*)(ws + W_1A); mode = 1; break;
;             case 1: W = P.in[5] + (size_t)l * DFF * DM; K = DFF; N = DM; WT = (bf16_t*)(ws + W_2A); break;
;             case 2: W = P.in[6] + (size_t)l * DM * ZLD; K = DM; N = ZLD; WT = (bf16_t*)(ws + W_Z); break;
;             case 3: W = P.in[18] + (size_t)l * DM * 3 * DM; K = DM; N = 3 * DM; WT = (bf16_t*)(ws + W_G); break;
;             case 4: W = P.in[15] + (size_t)l * 512 * DM; K = 512; N = DM; WT = (bf16_t*)(ws + W_BR); break;
;             case 5: W = P.in[16] + (size_t)l * 512 * DM; K = 512; N = DM; WT = (bf16_t*)(ws + W_BR) + 1 * DM * 512; break;
;             case 6: W = P.in[17] + (size_t)l * 512 * DM; K = 512; N = DM; WT = (bf16_t*)(ws + W_BR) + 2 * DM * 512; break;
;             case 7: W = P.in[20] + (size_t)l * DM * DM; K = DM; N = DM; WT = (bf16_t*)(ws + W_O); break;
;             case 8: W = P.in[23] + (size_t)l * DM * 2 * DFF; K = DM; N = 2 * DFF; WT = (bf16_t*)(ws + W_1B); mode = 1; break;
;             case 9: W = P.in[24] + (size_t)l * DFF * DM; K = DFF; N = DM; WT = (bf16_t*)(ws + W_2B); break;
;             case 10: W = P.in[9] + (size_t)l * 2048 * 256; K = 2048; N = 256; WT = (bf16_t*)(ws + W_C1); break;
;             case 11: W = P.in[11] + (size_t)l * 2048 * 256; K = 2048; N = 256; WT = (bf16_t*)(ws + W_C1) + 256 * 2048; break;
;             case 12: W = P.in[10] + (size_t)l * 256 * 64; K = 256; N = 64; WT = (bf16_t*)(ws + W_C2); break;
;             default: W = P.in[12] + (size_t)l * 256 * 64; K = 256; N = 64; WT = (bf16_t*)(ws + W_C2) + 64 * 256; break;
;         }
.LBB0_742:
	s_waitcnt vmcnt(0)
	v_readlane_b32 s36, v255, 11
	s_barrier
	v_readlane_b32 s0, v252, 40
	s_cmpk_lt_u32 s0, 0x400
	s_cbranch_scc1 .Lpw2_done
	v_mov_b32_e32 v13, v193
	v_readlane_b32 s0, v252, 40
	v_bfe_u32 v19, v13, 3, 3
	v_lshlrev_b32_e32 v0, 2, v13
	v_and_b32_e32 v0, 28, v0
	v_mul_u32_u24_e32 v2, 33, v19
	v_add_lshl_u32 v20, v2, v0, 2
	v_lshlrev_b32_e32 v2, 3, v13
	v_and_b32_e32 v2, 56, v2
	v_ashrrev_i32_e32 v3, 6, v13
	v_mul_u32_u24_e32 v6, 33, v2
	v_add_u32_e32 v15, s0, v3
	v_add_u32_e32 v15, 0xfffffc00, v15
	s_movk_i32 s0, 0x2200
	v_or_b32_e32 v21, 8, v19
	v_or_b32_e32 v22, 16, v19
	v_or_b32_e32 v23, 24, v19
	v_or_b32_e32 v8, v6, v19
	v_mul_lo_u32 v18, v3, s0
	v_add_u32_e32 v4, 0x420, v20
	v_add_u32_e32 v5, 0x840, v20
	v_add_u32_e32 v7, 0xc60, v20
	v_lshlrev_b32_e32 v8, 2, v8
	v_add_lshl_u32 v9, v6, v21, 2
	v_add_lshl_u32 v10, v6, v22, 2
	v_add_lshl_u32 v11, v6, v23, 2
	v_readlane_b32 s0, v255, 7
	s_mov_b32 s5, 7
	s_mov_b32 s99, 0
	v_lshlrev_b32_e32 v0, 2, v0
	v_lshl_add_u32 v24, v3, 5, s0
	v_lshlrev_b32_e32 v6, 1, v2
	v_add_u32_e32 v25, v18, v4
	v_add_u32_e32 v26, v18, v5
	v_add_u32_e32 v27, v18, v7
	v_add_u32_e32 v28, v18, v8
	v_add_u32_e32 v29, v18, v9
	v_add_u32_e32 v30, v18, v10
	v_add_u32_e32 v31, v18, v11
	s_branch .Lpw2_884
.Lpw2_883:
	s_or_b64 exec, exec, s[2:3]
	s_add_i32 s5, s5, 1
	s_cmp_eq_u32 s5, 10
	s_cbranch_scc1 .Lpw2_done

; __device__ __forceinline__ unsigned cvt_pk(float lo, float hi) { f32x2_t v = {lo, hi}; bf16x2_t b = __builtin_convertvector(v, bf16x2_t); return __builtin_bit_cast(unsigned, b); }
; __device__ __forceinline__ void tr_item(const float* W, int ldw, int K, int k0, int n0, bf16_t* WT, int drow0, lptr scr, int lane) {
;     f32x4 tv[8];
; #pragma unroll
;     for (int i = 0; i < 8; ++i) tv[i] = *(const f32x4*)(W + (size_t)(k0 + 8 * i + (lane >> 3)) * ldw + n0 + 4 * (lane & 7));
; #pragma unroll
;     for (int i = 0; i < 8; ++i) {
;         const lptr d_ = scr + ((8 * i + (lane >> 3)) * 33 + 4 * (lane & 7)) * 4;
;         lds_st<float>(d_, tv[i][0]); lds_st<float>(d_ + 4, tv[i][1]); lds_st<float>(d_ + 8, tv[i][2]); lds_st<float>(d_ + 12, tv[i][3]);
;     }
;     const int c = lane & 7;
; #pragma unroll
;     for (int j = 0; j < 4; ++j) {
;         const int n = (lane >> 3) + 8 * j; const lptr s = scr + ((8 * c) * 33 + n) * 4;
;         u32x4 o; o.x = cvt_pk(lds_ld<float>(s), lds_ld<float>(s + 33 * 4)); o.y = cvt_pk(lds_ld<float>(s + 2 * 33 * 4), lds_ld<float>(s + 3 * 33 * 4));
;         o.z = cvt_pk(lds_ld<float>(s + 4 * 33 * 4), lds_ld<float>(s + 5 * 33 * 4)); o.w = cvt_pk(lds_ld<float>(s + 6 * 33 * 4), lds_ld<float>(s + 7 * 33 * 4));
;         *(u32x4*)(WT + (size_t)(drow0 + n) * K + k0 + 8 * c) = o;
;     }
; }
; __device__ __forceinline__ void prep_weights(lptr L, const Params& P, int l) {
;     ...
;         const int nblk = N / 32, nitems = (K / 64) * nblk;
;         for (int it = gw; it < nitems; it += NGW) {
;             const int kb = it / nblk, nb = it - kb * nblk, n0 = 32 * nb;
;             int drow0 = n0;
;             if (mode == 1) { const int up = n0 >= DFF, nn = up ? n0 - DFF : n0; drow0 = 256 * (nn >> 7) + (up ? 128 : 0) + (nn & 127); }
;             tr_item(W, N, K, 64 * kb, n0, WT, drow0, scr, lane);
;         }
.Lpw2_932:
	s_lshr_b32 s14, s10, 5
	s_lshr_b32 s18, s13, 6
	s_mul_i32 s18, s18, s14
	s_movk_i32 s30, 0x3ff
	v_subrev_u32_e32 v14, s99, v15
	v_and_b32_e32 v14, s30, v14
	s_add_i32 s99, s99, s18
	v_cmp_gt_i32_e32 vcc, s18, v14
	s_and_saveexec_b64 s[2:3], vcc
	s_cbranch_execz .Lpw2_883
	v_cvt_f32_u32_e32 v2, s14
	v_mov_b32_e32 v7, v1
	v_lshl_add_u64 v[10:11], s[26:27], 0, v[6:7]
	s_sub_i32 s26, 0, s14
	v_rcp_iflag_f32_e32 v2, v2
	v_lshl_add_u64 v[8:9], s[6:7], 0, v[0:1]
	s_lshl_b32 s6, s14, 5
	s_sub_i32 s27, 0, s6
	v_mul_f32_e32 v2, 0x4f7ffffe, v2
	v_cvt_u32_f32_e32 v2, v2
	s_mov_b64 s[6:7], 0
	v_lshlrev_b32_e32 v12, 5, v14
	v_mul_lo_u32 v3, s26, v2
	v_mul_hi_u32 v3, v2, v3
	v_add_u32_e32 v7, v2, v3
	s_branch .Lpw2_935
.Lpw2_934:
	v_lshlrev_b32_e32 v16, 6, v4
	v_or_b32_e32 v33, v16, v19
	v_ashrrev_i32_e32 v3, 31, v2
	v_ashrrev_i32_e32 v17, 31, v16
	v_lshl_add_u64 v[58:59], v[2:3], 2, v[8:9]
	v_mul_lo_u32 v62, v17, s10
	v_mad_u64_u32 v[2:3], s[30:31], v33, s10, 0
	v_or_b32_e32 v46, 32, v33
	v_add_u32_e32 v3, v3, v62
	v_or_b32_e32 v34, 8, v33
	v_mad_u64_u32 v[46:47], s[30:31], v46, s10, 0
	v_lshl_add_u64 v[2:3], v[2:3], 2, v[58:59]
	v_mad_u64_u32 v[34:35], s[30:31], v34, s10, 0
	v_add_u32_e32 v47, v47, v62
	v_or_b32_e32 v50, 40, v33
	global_load_dwordx4 v[2:5], v[2:3], off
	v_add_u32_e32 v35, v35, v62
	v_or_b32_e32 v38, 16, v33
	v_lshl_add_u64 v[46:47], v[46:47], 2, v[58:59]
	v_mad_u64_u32 v[50:51], s[30:31], v50, s10, 0
	v_lshl_add_u64 v[34:35], v[34:35], 2, v[58:59]
	v_mad_u64_u32 v[38:39], s[30:31], v38, s10, 0
	global_load_dwordx4 v[46:49], v[46:47], off
	v_add_u32_e32 v51, v51, v62
	v_or_b32_e32 v54, 48, v33
	global_load_dwordx4 v[34:37], v[34:35], off
	v_add_u32_e32 v39, v39, v62
	v_or_b32_e32 v42, 24, v33
	v_lshl_add_u64 v[50:51], v[50:51], 2, v[58:59]
	v_mad_u64_u32 v[54:55], s[30:31], v54, s10, 0
	v_lshl_add_u64 v[38:39], v[38:39], 2, v[58:59]
	v_mad_u64_u32 v[42:43], s[30:31], v42, s10, 0
	global_load_dwordx4 v[50:53], v[50:51], off
	v_add_u32_e32 v55, v55, v62
	v_or_b32_e32 v33, 56, v33
	global_load_dwordx4 v[38:41], v[38:39], off
	v_add_u32_e32 v43, v43, v62
	v_lshl_add_u64 v[54:55], v[54:55], 2, v[58:59]
	v_mad_u64_u32 v[60:61], s[30:31], v33, s10, 0
	v_lshl_add_u64 v[42:43], v[42:43], 2, v[58:59]
	global_load_dwordx4 v[54:57], v[54:55], off
	v_add_u32_e32 v61, v61, v62
	global_load_dwordx4 v[42:45], v[42:43], off
	v_lshl_add_u64 v[58:59], v[60:61], 2, v[58:59]
	global_load_dwordx4 v[58:61], v[58:59], off
	v_add_u32_e32 v33, v18, v20
	v_lshl_add_u64 v[16:17], v[16:17], 1, v[10:11]
	v_add_u32_e32 v14, 0x400, v14
	v_cmp_le_i32_e32 vcc, s18, v14
	v_add_u32_e32 v12, 0x8000, v12
	s_or_b64 s[6:7], vcc, s[6:7]
	s_waitcnt vmcnt(0)
	ds_write2_b32 v33, v2, v3 offset1:1
	ds_write2_b32 v33, v4, v5 offset0:2 offset1:3
	ds_write2_b32 v25, v34, v35 offset1:1
	ds_write2_b32 v25, v36, v37 offset0:2 offset1:3
	ds_write2_b32 v26, v38, v39 offset1:1
	ds_write2_b32 v26, v40, v41 offset0:2 offset1:3
	ds_write2_b32 v27, v42, v43 offset1:1
	ds_write2_b32 v27, v44, v45 offset0:2 offset1:3
	v_add_u32_e32 v2, 0x1080, v33
	ds_write2_b32 v2, v46, v47 offset1:1
	v_add_u32_e32 v2, 0x1088, v33
	ds_write2_b32 v2, v48, v49 offset1:1
	v_add_u32_e32 v2, 0x14a0, v33
	ds_write2_b32 v2, v50, v51 offset1:1
	v_add_u32_e32 v2, 0x14a8, v33
	ds_write2_b32 v2, v52, v53 offset1:1
	v_add_u32_e32 v2, 0x18c0, v33
	ds_write2_b32 v2, v54, v55 offset1:1
	v_add_u32_e32 v2, 0x18c8, v33
	ds_write2_b32 v2, v56, v57 offset1:1
	v_add_u32_e32 v2, 0x1ce0, v33
	ds_write2_b32 v2, v58, v59 offset1:1
	v_add_u32_e32 v2, 0x1ce8, v33
	ds_write2_b32 v2, v60, v61 offset1:1
	ds_read2_b32 v[2:3], v28 offset1:33
	ds_read2_b32 v[4:5], v28 offset0:66 offset1:99
	ds_read2_b32 v[34:35], v28 offset0:198 offset1:231
	v_add_u32_e32 v33, v32, v19
	v_ashrrev_i32_e32 v37, 31, v33
	s_waitcnt lgkmcnt(2)
	v_cvt_pk_bf16_f32 v2, v2, v3
	s_waitcnt lgkmcnt(1)
	v_cvt_pk_bf16_f32 v3, v4, v5
	ds_read2_b32 v[4:5], v28 offset0:132 offset1:165
	s_waitcnt lgkmcnt(0)
	v_cvt_pk_bf16_f32 v4, v4, v5
	v_cvt_pk_bf16_f32 v5, v34, v35
	v_mad_u64_u32 v[34:35], s[30:31], v33, s13, 0
	v_mov_b32_e32 v36, v35
	v_mad_u64_u32 v[36:37], s[30:31], v37, s13, v[36:37]
	v_mov_b32_e32 v35, v36
	v_lshl_add_u64 v[34:35], v[34:35], 1, v[16:17]
	global_store_dwordx4 v[34:35], v[2:5], off
	ds_read2_b32 v[2:3], v29 offset1:33
	ds_read2_b32 v[4:5], v29 offset0:66 offset1:99
	ds_read2_b32 v[34:35], v29 offset0:198 offset1:231
	v_add_u32_e32 v33, v32, v21
	v_ashrrev_i32_e32 v37, 31, v33
	s_waitcnt lgkmcnt(2)
	v_cvt_pk_bf16_f32 v2, v2, v3
	s_waitcnt lgkmcnt(1)
	v_cvt_pk_bf16_f32 v3, v4, v5
	ds_read2_b32 v[4:5], v29 offset0:132 offset1:165
	s_waitcnt lgkmcnt(0)
	v_cvt_pk_bf16_f32 v4, v4, v5
	v_cvt_pk_bf16_f32 v5, v34, v35
	v_mad_u64_u32 v[34:35], s[30:31], v33, s13, 0
	v_mov_b32_e32 v36, v35
	v_mad_u64_u32 v[36:37], s[30:31], v37, s13, v[36:37]
	v_mov_b32_e32 v35, v36
	v_lshl_add_u64 v[34:35], v[34:35], 1, v[16:17]
	global_store_dwordx4 v[34:35], v[2:5], off
	ds_read2_b32 v[2:3], v30 offset1:33
	ds_read2_b32 v[4:5], v30 offset0:66 offset1:99
	ds_read2_b32 v[34:35], v30 offset0:198 offset1:231
	v_add_u32_e32 v33, v32, v22
	v_ashrrev_i32_e32 v37, 31, v33
	s_waitcnt lgkmcnt(2)
	v_cvt_pk_bf16_f32 v2, v2, v3
	s_waitcnt lgkmcnt(1)
	v_cvt_pk_bf16_f32 v3, v4, v5
	ds_read2_b32 v[4:5], v30 offset0:132 offset1:165
	v_add_u32_e32 v32, v32, v23
	s_waitcnt lgkmcnt(0)
	v_cvt_pk_bf16_f32 v4, v4, v5
	v_cvt_pk_bf16_f32 v5, v34, v35
	v_mad_u64_u32 v[34:35], s[30:31], v33, s13, 0
	v_mov_b32_e32 v36, v35
	v_mad_u64_u32 v[36:37], s[30:31], v37, s13, v[36:37]
	v_mov_b32_e32 v35, v36
	v_lshl_add_u64 v[34:35], v[34:35], 1, v[16:17]
	global_store_dwordx4 v[34:35], v[2:5], off
	ds_read2_b32 v[2:3], v31 offset1:33
	ds_read2_b32 v[4:5], v31 offset0:66 offset1:99
	ds_read2_b32 v[34:35], v31 offset0:198 offset1:231
	s_waitcnt lgkmcnt(2)
	v_cvt_pk_bf16_f32 v2, v2, v3
	s_waitcnt lgkmcnt(1)
	v_cvt_pk_bf16_f32 v3, v4, v5
	ds_read2_b32 v[4:5], v31 offset0:132 offset1:165
	s_waitcnt lgkmcnt(0)
	v_cvt_pk_bf16_f32 v4, v4, v5
	v_cvt_pk_bf16_f32 v5, v34, v35
	v_ashrrev_i32_e32 v35, 31, v32
	v_mad_u64_u32 v[32:33], s[30:31], v32, s13, 0
	v_mov_b32_e32 v34, v33
	v_mad_u64_u32 v[34:35], s[30:31], v35, s13, v[34:35]
	v_mov_b32_e32 v33, v34
	v_lshl_add_u64 v[16:17], v[32:33], 1, v[16:17]
	global_store_dwordx4 v[16:17], v[2:5], off
	s_andn2_b64 exec, exec, s[6:7]
	s_cbranch_execz .Lpw2_883

; #define PG8_LAS __attribute__((address_space(3)))
; __global__ void __launch_bounds__(NT, 2) mk_fwd(Params P) {
;     ...
;                 pg8::Gemm g{XN, (const bf16_t*)(ws + W_Z), M, 3840, DM}; pg8::StaticOrder S; S.init(M, 3840, G, bx);
;                 EpiZ E{BIG};
;                 pg8::gemm_phase<EpiZ, pg8::StaticOrder, true, true>((PG8_LAS unsigned char*)L, g, S, E);
.Lpw2_done:
.LBB0_743:
	s_mov_b64 s[82:83], 0

; __device__ __forceinline__ void prep_weights(lptr L, const Params& P, int l) {
;     ...
;     for (int mi = 0; mi < 14; ++mi) {
;         const float* W; int K, N, mode = 0; bf16_t* WT;
;         switch (mi) {
;             case 0: W = P.in[4] + (size_t)l * DM * 2 * DFF; K = DM; N = 2 * DFF; WT = (bf16_t*)(ws + W_1A); mode = 1; break;
;             case 1: W = P.in[5] + (size_t)l * DFF * DM; K = DFF; N = DM; WT = (bf16_t*)(ws + W_2A); break;
;             case 2: W = P.in[6] + (size_t)l * DM * ZLD; K = DM; N = ZLD; WT = (bf16_t*)(ws + W_Z); break;
;             case 3: W = P.in[18] + (size_t)l * DM * 3 * DM; K = DM; N = 3 * DM; WT = (bf16_t*)(ws + W_G); break;
;             case 4: W = P.in[15] + (size_t)l * 512 * DM; K = 512; N = DM; WT = (bf16_t*)(ws + W_BR); break;
;             case 5: W = P.in[16] + (size_t)l * 512 * DM; K = 512; N = DM; WT = (bf16_t*)(ws + W_BR) + 1 * DM * 512; break;
;             case 6: W = P.in[17] + (size_t)l * 512 * DM; K = 512; N = DM; WT = (bf16_t*)(ws + W_BR) + 2 * DM * 512; break;
;             case 7: W = P.in[20] + (size_t)l * DM * DM; K = DM; N = DM; WT = (bf16_t*)(ws + W_O); break;
;             case 8: W = P.in[23] + (size_t)l * DM * 2 * DFF; K = DM; N = 2 * DFF; WT = (bf16_t*)(ws + W_1B); mode = 1; break;
;             case 9: W = P.in[24] + (size_t)l * DFF * DM; K = DFF; N = DM; WT = (bf16_t*)(ws + W_2B); break;
;             case 10: W = P.in[9] + (size_t)l * 2048 * 256; K = 2048; N = 256; WT = (bf16_t*)(ws + W_C1); break;
;             case 11: W = P.in[11] + (size_t)l * 2048 * 256; K = 2048; N = 256; WT = (bf16_t*)(ws + W_C1) + 256 * 2048; break;
;             case 12: W = P.in[10] + (size_t)l * 256 * 64; K = 256; N = 64; WT = (bf16_t*)(ws + W_C2); break;
;             default: W = P.in[12] + (size_t)l * 256 * 64; K = 256; N = 64; WT = (bf16_t*)(ws + W_C2) + 64 * 256; break;
;         }
.LBB0_883:
	s_or_b64 exec, exec, s[2:3]
	s_add_i32 s5, s5, 1
	s_cmp_eq_u32 s5, 7
	s_cselect_b32 s5, 10, s5
	s_cmp_eq_u32 s5, 14
	s_cbranch_scc1 .LBB0_937
